# grid barrier: agent-scope L1 invalidate issued at arrival (overlaps the wait) instead of after the release
# speedup vs baseline: 1.0300x; 1.0013x over previous
; __device__ __forceinline__ unsigned xb_add(unsigned* p, unsigned v) { return __hip_atomic_fetch_add(p, v, __ATOMIC_RELAXED, __HIP_MEMORY_SCOPE_AGENT); }
; __device__ __forceinline__ void xcd_barrier(const XcdBarrier& b) {
;     ...
;         const unsigned old = xb_add(&bar[XB_XSUB(b.x)], 1u);
;         const unsigned gen = old / nloc;
;         if (old + 1u == (gen + 1u) * nloc) {
.LBB0_1148:
	s_or_b64 exec, exec, s[2:3]
	v_cvt_f32_u32_e32 v4, v2
	s_waitcnt vmcnt(0)
	v_readfirstlane_b32 s2, v3
	v_sub_u32_e32 v3, 0, v2
	v_rcp_iflag_f32_e32 v4, v4
	v_add_u32_e32 v5, s2, v1
	v_mul_f32_e32 v4, 0x4f7ffffe, v4
	v_cvt_u32_f32_e32 v4, v4
	v_mul_lo_u32 v1, v3, v4
	v_mul_hi_u32 v1, v4, v1
	v_add_u32_e32 v1, v4, v1
	v_mul_hi_u32 v1, v5, v1
	v_mul_lo_u32 v3, v1, v2
	v_sub_u32_e32 v3, v5, v3
	v_add_u32_e32 v4, 1, v1
	v_cmp_ge_u32_e32 vcc, v3, v2
	s_nop 1
	v_cndmask_b32_e32 v1, v1, v4, vcc
	v_sub_u32_e32 v4, v3, v2
	v_cndmask_b32_e32 v3, v3, v4, vcc
	v_add_u32_e32 v4, 1, v1
	v_cmp_ge_u32_e32 vcc, v3, v2
	v_add_u32_e32 v3, 1, v5
	s_nop 0
	v_cndmask_b32_e32 v1, v1, v4, vcc
	v_mul_lo_u32 v4, v2, v1
	v_add_u32_e32 v2, v4, v2
	v_cmp_ne_u32_e32 vcc, v3, v2
	s_and_saveexec_b64 s[2:3], vcc
	s_xor_b64 s[18:19], exec, s[2:3]
	s_cbranch_execz .LBB0_1162
	buffer_inv sc1
	v_readlane_b32 s2, v254, 42

; __device__ __forceinline__ unsigned xb_ld(unsigned* p)              { return __hip_atomic_load(p, __ATOMIC_RELAXED, __HIP_MEMORY_SCOPE_AGENT); }
; #define XB_SPIN(cond, bar) do { unsigned _sp = 0; while (cond) { __builtin_amdgcn_s_sleep(1); \
;     if ((++_sp & 255u) == 0u) { if (xb_ld(&(bar)[XB_TMO])) break; if (_sp > XB_SPIN_CAP) { atomicAdd(&(bar)[XB_TMO], 1u); break; } } } } while (0)
; __device__ __forceinline__ void xcd_barrier(const XcdBarrier& b) {
;     ...
;         } else {
;             XB_SPIN(xb_ld(&bar[XB_XGEN(b.x)]) == gen, bar);
;             __builtin_amdgcn_fence(__ATOMIC_ACQUIRE, "agent");
	v_readlane_b32 s3, v254, 43
	s_waitcnt lgkmcnt(0)
	s_nop 3
	global_load_dword v0, v181, s[2:3] sc1
	s_waitcnt vmcnt(0)
	v_cmp_eq_u32_e32 vcc, v0, v1
	s_and_saveexec_b64 s[38:39], vcc
	s_cbranch_execz .LBB0_1161
	s_mov_b32 s4, 1
	s_mov_b64 s[40:41], 0
	s_branch .LBB0_1152

; __device__ __forceinline__ unsigned xb_ld(unsigned* p)              { return __hip_atomic_load(p, __ATOMIC_RELAXED, __HIP_MEMORY_SCOPE_AGENT); }
; __device__ __forceinline__ unsigned xb_add(unsigned* p, unsigned v) { return __hip_atomic_fetch_add(p, v, __ATOMIC_RELAXED, __HIP_MEMORY_SCOPE_AGENT); }
; #define XB_SPIN(cond, bar) do { unsigned _sp = 0; while (cond) { __builtin_amdgcn_s_sleep(1); \
;     if ((++_sp & 255u) == 0u) { if (xb_ld(&(bar)[XB_TMO])) break; if (_sp > XB_SPIN_CAP) { atomicAdd(&(bar)[XB_TMO], 1u); break; } } } } while (0)
; __device__ __forceinline__ void xcd_barrier(const XcdBarrier& b) {
;     ...
;             __builtin_amdgcn_fence(__ATOMIC_RELEASE, "agent");
;             asm volatile("s_waitcnt vmcnt(0)" ::: "memory");
;             const unsigned og = xb_add(&bar[XB_TOP], 1u);
;             const unsigned tg = og / nx;
;             if (og + 1u == (tg + 1u) * nx) xb_add(&bar[XB_TOPGEN], 1u);
;             else XB_SPIN(xb_ld(&bar[XB_TOPGEN]) == tg, bar);
;             __builtin_amdgcn_fence(__ATOMIC_ACQUIRE, "agent");
;             xb_add(&bar[XB_XGEN(b.x)], 1u);
;             asm volatile("s_waitcnt vmcnt(0)" ::: "memory");
;         } else {
;             XB_SPIN(xb_ld(&bar[XB_XGEN(b.x)]) == gen, bar);
;             __builtin_amdgcn_fence(__ATOMIC_ACQUIRE, "agent");
;             asm volatile("s_waitcnt vmcnt(0)" ::: "memory");
.LBB0_1161:
	s_or_b64 exec, exec, s[38:39]
	s_waitcnt vmcnt(0)
	s_waitcnt vmcnt(0)
.LBB0_1162:
	s_andn2_saveexec_b64 s[2:3], s[18:19]
	s_cbranch_execz .LBB0_17
	s_mov_b64 s[2:3], exec
	buffer_wbl2 sc1
	buffer_inv sc1

; __device__ __forceinline__ unsigned xb_add(unsigned* p, unsigned v) { return __hip_atomic_fetch_add(p, v, __ATOMIC_RELAXED, __HIP_MEMORY_SCOPE_AGENT); }
; __device__ __forceinline__ void xcd_barrier(const XcdBarrier& b) {
;     ...
;             __builtin_amdgcn_fence(__ATOMIC_RELEASE, "agent");
;             asm volatile("s_waitcnt vmcnt(0)" ::: "memory");
;             const unsigned og = xb_add(&bar[XB_TOP], 1u);
;             const unsigned tg = og / nx;
	s_waitcnt lgkmcnt(0)
	s_waitcnt vmcnt(0)
	v_mbcnt_lo_u32_b32 v1, s2, 0
	v_mbcnt_hi_u32_b32 v1, s3, v1
	v_cmp_eq_u32_e32 vcc, 0, v1
	s_and_saveexec_b64 s[18:19], vcc
	s_cbranch_execz .LBB0_1165
	s_bcnt1_i32_b64 s2, s[2:3]
	v_mov_b32_e32 v2, s2
	v_readlane_b32 s2, v254, 44
	v_readlane_b32 s3, v254, 45
	s_nop 4
	global_atomic_add v2, v181, v2, s[2:3] sc0

; __device__ __forceinline__ unsigned xb_ld(unsigned* p)              { return __hip_atomic_load(p, __ATOMIC_RELAXED, __HIP_MEMORY_SCOPE_AGENT); }
; __device__ __forceinline__ unsigned xb_add(unsigned* p, unsigned v) { return __hip_atomic_fetch_add(p, v, __ATOMIC_RELAXED, __HIP_MEMORY_SCOPE_AGENT); }
; #define XB_SPIN(cond, bar) do { unsigned _sp = 0; while (cond) { __builtin_amdgcn_s_sleep(1); \
;     if ((++_sp & 255u) == 0u) { if (xb_ld(&(bar)[XB_TMO])) break; if (_sp > XB_SPIN_CAP) { atomicAdd(&(bar)[XB_TMO], 1u); break; } } } } while (0)
; __device__ __forceinline__ void xcd_barrier(const XcdBarrier& b) {
;     ...
;             __builtin_amdgcn_fence(__ATOMIC_ACQUIRE, "agent");
;             xb_add(&bar[XB_XGEN(b.x)], 1u);
;             asm volatile("s_waitcnt vmcnt(0)" ::: "memory");
;         } else {
;             XB_SPIN(xb_ld(&bar[XB_XGEN(b.x)]) == gen, bar);
;             __builtin_amdgcn_fence(__ATOMIC_ACQUIRE, "agent");
;             asm volatile("s_waitcnt vmcnt(0)" ::: "memory");
;         }
;     }
;     __syncthreads();
.LBB0_1179:
	s_or_b64 exec, exec, s[2:3]
	s_mov_b64 s[2:3], exec
	v_mbcnt_lo_u32_b32 v0, s2, 0
	v_mbcnt_hi_u32_b32 v0, s3, v0
	v_cmp_eq_u32_e32 vcc, 0, v0
	s_waitcnt vmcnt(0)
	s_and_saveexec_b64 s[18:19], vcc
	s_cbranch_execz .LBB0_16
	s_branch .LBB0_16
